# replace 16 in-loop cooperative-groups grid syncs with 2-level atomic barrier in ws (8 groups x 32 WGs); first sync stays cg
# speedup vs baseline: 1.2703x; 1.2703x over previous
.LBB0_40:
	s_or_b64 exec, exec, s[0:1]
	s_cmp_lg_u32 s59, 0
	s_cbranch_scc1 .Lgs_init_done
	v_cmp_eq_u32_e32 vcc, 0, v174
	s_and_saveexec_b64 s[4:5], vcc
	s_cbranch_execz .Lgs_init_skip
	s_add_u32 s0, s56, 0x2480000
	s_addc_u32 s1, s57, 0
	v_mov_b32_e32 v1, 0
	v_mov_b32_e32 v2, 0
	v_mov_b32_e32 v3, 0x1000
	s_nop 0
	global_atomic_and v1, v2, s[0:1]
	global_atomic_and v1, v2, s[0:1] offset:256
	global_atomic_and v1, v2, s[0:1] offset:512
	global_atomic_and v1, v2, s[0:1] offset:768
	global_atomic_and v1, v2, s[0:1] offset:1024
	global_atomic_and v1, v2, s[0:1] offset:1280
	global_atomic_and v1, v2, s[0:1] offset:1536
	global_atomic_and v1, v2, s[0:1] offset:1792
	global_atomic_and v1, v2, s[0:1] offset:2048
	global_atomic_and v1, v2, s[0:1] offset:2304
	global_atomic_and v1, v2, s[0:1] offset:2560
	global_atomic_and v1, v2, s[0:1] offset:2816
	global_atomic_and v1, v2, s[0:1] offset:3072
	global_atomic_and v1, v2, s[0:1] offset:3328
	global_atomic_and v1, v2, s[0:1] offset:3584
	global_atomic_and v1, v2, s[0:1] offset:3840
	global_atomic_and v3, v2, s[0:1]
	s_waitcnt vmcnt(0)

.Lgs_init_done:
	s_waitcnt vmcnt(0) lgkmcnt(0)
	v_lshrrev_b32_e32 v1, 20, v0
	v_lshrrev_b32_e32 v0, 10, v0
	v_or_b32_e32 v0, v0, v1
	s_movk_i32 s0, 0x3ff
	v_and_or_b32 v0, v0, s0, v174
	s_barrier
	v_cmp_eq_u32_e64 s[0:1], 0, v0
	s_mov_b64 s[4:5], exec
	s_nop 0
	v_writelane_b32 v255, s0, 28
	s_nop 1
	v_writelane_b32 v255, s1, 29
	s_and_b64 s[0:1], s[4:5], s[0:1]
	s_mov_b64 exec, s[0:1]
	s_cbranch_execz .LBB0_50
	v_readlane_b32 s0, v255, 16
	v_readlane_b32 s1, v255, 17
	buffer_wbl2 sc1
	s_waitcnt vmcnt(0)
	s_load_dwordx2 s[6:7], s[0:1], 0x58
	v_mov_b32_e32 v2, 0
	s_mov_b64 s[8:9], exec
	v_mbcnt_lo_u32_b32 v1, s8, 0
	v_mbcnt_hi_u32_b32 v1, s9, v1
	s_waitcnt lgkmcnt(0)
	global_load_dword v0, v2, s[6:7] offset:40
	v_cmp_eq_u32_e32 vcc, 0, v1
	s_and_saveexec_b64 s[10:11], vcc
	s_cbranch_execz .LBB0_43
	s_bcnt1_i32_b64 s0, s[8:9]
	v_mov_b32_e32 v3, s0
	global_atomic_add v3, v2, v3, s[6:7] offset:32 sc0

.LBB0_66:
	s_or_b64 exec, exec, s[6:7]
	s_waitcnt vmcnt(0) lgkmcnt(0)
	s_barrier
	s_mov_b64 s[4:5], exec
	v_readlane_b32 s0, v255, 30
	v_readlane_b32 s1, v255, 31
	s_and_b64 s[0:1], s[4:5], s[0:1]
	s_mov_b64 exec, s[0:1]
	s_cbranch_execz .Lgs2_done
	s_mov_b64 exec, 1
	v_readlane_b32 s6, v255, 40
	v_readlane_b32 s7, v255, 41
	v_readlane_b32 s8, v255, 42
	s_nop 3
	s_add_u32 s6, s6, 0x2480000
	s_addc_u32 s7, s7, 0
	s_and_b32 s8, s8, 7
	s_lshl_b32 s8, s8, 8
	v_mov_b32_e32 v0, s8
	v_mov_b32_e32 v2, 1
	s_nop 1
	global_load_dword v3, v0, s[6:7] offset:2048 sc1
	buffer_wbl2 sc1
	s_waitcnt vmcnt(0)
	global_atomic_add v2, v0, v2, s[6:7] sc0
	s_waitcnt vmcnt(0)
	v_readfirstlane_b32 s9, v2
	v_readfirstlane_b32 s10, v3
	s_and_b32 s9, s9, 31
	s_cmp_lg_u32 s9, 31
	s_cbranch_scc1 .Lgs2_poll
	v_mov_b32_e32 v2, 1
	v_mov_b32_e32 v3, 0x1000
	s_nop 1
	global_atomic_add v2, v3, v2, s[6:7] sc0
	s_waitcnt vmcnt(0)
	v_readfirstlane_b32 s9, v2
	s_and_b32 s9, s9, 7
	s_cmp_lg_u32 s9, 7
	s_cbranch_scc1 .Lgs2_poll
	v_mov_b32_e32 v2, 1
	v_mov_b32_e32 v3, 0
	s_nop 1
	global_atomic_add v3, v2, s[6:7] offset:2048
	global_atomic_add v3, v2, s[6:7] offset:2304
	global_atomic_add v3, v2, s[6:7] offset:2560
	global_atomic_add v3, v2, s[6:7] offset:2816
	global_atomic_add v3, v2, s[6:7] offset:3072
	global_atomic_add v3, v2, s[6:7] offset:3328
	global_atomic_add v3, v2, s[6:7] offset:3584
	global_atomic_add v3, v2, s[6:7] offset:3840
.Lgs2_poll:
	s_mov_b32 s11, 0
.Lgs2_spin:
	global_load_dword v2, v0, s[6:7] offset:2048 sc1
	s_waitcnt vmcnt(0)
	v_readfirstlane_b32 s9, v2
	s_cmp_lg_u32 s9, s10
	s_cbranch_scc1 .Lgs2_rel
	s_add_u32 s11, s11, 1
	s_cmp_lt_u32 s11, 0x8000
	s_cbranch_scc0 .Lgs2_rel
	s_sleep 1
	s_branch .Lgs2_spin
.Lgs2_rel:
	s_mov_b64 exec, s[0:1]
	buffer_inv sc1
	s_waitcnt vmcnt(0)
.Lgs2_done:
	s_mov_b64 exec, s[4:5]
	v_readlane_b32 s4, v255, 20
	s_mov_b32 s58, s59
	v_readlane_b32 s10, v255, 26
	v_readlane_b32 s11, v255, 27
	s_barrier
	v_readlane_b32 s5, v255, 21
	v_readlane_b32 s6, v255, 22
	s_mov_b64 s[76:77], s[10:11]
	v_mov_b32_e32 v11, v174
	s_cmpk_lt_i32 s58, 0x2a0
	s_cselect_b64 s[4:5], -1, 0
	s_cmpk_gt_i32 s58, 0x29f
	v_readfirstlane_b32 s6, v11
	v_readlane_b32 s7, v255, 23
	v_readlane_b32 s8, v255, 24
	v_readlane_b32 s9, v255, 25
	s_cbranch_scc1 .LBB0_80
	s_ashr_i32 s0, s58, 31
	s_lshr_b32 s0, s0, 29
	s_add_i32 s0, s58, s0
	s_ashr_i32 s1, s0, 3
	s_and_b32 s0, s0, -8
	s_sub_i32 s0, s58, s0
	s_cmp_lt_i32 s0, 0
	s_cselect_b32 s2, s60, 0x54
	s_mul_i32 s0, s0, s2
	s_add_i32 s0, s0, s1
	s_mul_hi_i32 s1, s0, 0x92492493
	s_add_i32 s1, s1, s0
	s_lshr_b32 s2, s1, 31
	s_ashr_i32 s1, s1, 6
	s_add_i32 s1, s1, s2
	s_lshl_b32 s2, s1, 3
	s_mulk_i32 s1, 0x70
	s_sub_i32 s0, s0, s1
	s_bfe_i32 s1, s0, 0x80000
	s_bfe_u32 s1, s1, 0x3000c
	s_add_i32 s1, s0, s1
	s_bfe_i32 s7, s1, 0x80000
	s_and_b32 s1, s1, 0xf8
	s_sub_i32 s0, s0, s1
	s_sext_i32_i16 s7, s7
	s_sext_i32_i8 s0, s0
	s_add_i32 s10, s2, s0
	s_ashr_i32 s92, s7, 3

.LBB0_135:
	s_waitcnt vmcnt(0) lgkmcnt(0)
	s_waitcnt vmcnt(0)
	s_barrier
	s_mov_b64 s[4:5], exec
	v_readlane_b32 s0, v255, 30
	v_readlane_b32 s1, v255, 31
	s_and_b64 s[0:1], s[4:5], s[0:1]
	s_mov_b64 exec, s[0:1]
	s_cbranch_execz .Lgs3_done
	s_mov_b64 exec, 1
	v_readlane_b32 s6, v255, 40
	v_readlane_b32 s7, v255, 41
	v_readlane_b32 s8, v255, 42
	s_nop 3
	s_add_u32 s6, s6, 0x2480000
	s_addc_u32 s7, s7, 0
	s_and_b32 s8, s8, 7
	s_lshl_b32 s8, s8, 8
	v_mov_b32_e32 v0, s8
	v_mov_b32_e32 v2, 1
	s_nop 1
	global_load_dword v3, v0, s[6:7] offset:2048 sc1
	buffer_wbl2 sc1
	s_waitcnt vmcnt(0)
	global_atomic_add v2, v0, v2, s[6:7] sc0
	s_waitcnt vmcnt(0)
	v_readfirstlane_b32 s9, v2
	v_readfirstlane_b32 s10, v3
	s_and_b32 s9, s9, 31
	s_cmp_lg_u32 s9, 31
	s_cbranch_scc1 .Lgs3_poll
	v_mov_b32_e32 v2, 1
	v_mov_b32_e32 v3, 0x1000
	s_nop 1
	global_atomic_add v2, v3, v2, s[6:7] sc0
	s_waitcnt vmcnt(0)
	v_readfirstlane_b32 s9, v2
	s_and_b32 s9, s9, 7
	s_cmp_lg_u32 s9, 7
	s_cbranch_scc1 .Lgs3_poll
	v_mov_b32_e32 v2, 1
	v_mov_b32_e32 v3, 0
	s_nop 1
	global_atomic_add v3, v2, s[6:7] offset:2048
	global_atomic_add v3, v2, s[6:7] offset:2304
	global_atomic_add v3, v2, s[6:7] offset:2560
	global_atomic_add v3, v2, s[6:7] offset:2816
	global_atomic_add v3, v2, s[6:7] offset:3072
	global_atomic_add v3, v2, s[6:7] offset:3328
	global_atomic_add v3, v2, s[6:7] offset:3584
	global_atomic_add v3, v2, s[6:7] offset:3840

.Lgs3_done:
	s_mov_b64 exec, s[4:5]
	v_mov_b32_e32 v100, v174
	v_readlane_b32 s4, v255, 20
	s_movk_i32 s0, 0x744
	s_barrier
	s_mov_b64 s[76:77], s[56:57]
	v_readlane_b32 s5, v255, 21
	v_readlane_b32 s6, v255, 22
	v_readlane_b32 s7, v255, 23
	v_cmp_gt_i32_e32 vcc, s0, v100
	v_readlane_b32 s8, v255, 24
	v_readlane_b32 s9, v255, 25
	v_readlane_b32 s10, v255, 26
	v_readlane_b32 s11, v255, 27
	s_and_saveexec_b64 s[4:5], vcc
	s_cbranch_execz .LBB0_160
	s_mul_i32 s30, s34, 0x744
	v_max_i32_e32 v0, 0x544, v100
	s_lshl_b64 s[0:1], s[30:31], 2
	v_sub_u32_e32 v0, v0, v100
	s_add_u32 s6, s6, s0
	v_add_u32_e32 v0, 0x1ff, v0
	s_movk_i32 s0, 0x1ff
	s_addc_u32 s7, s7, s1
	v_cmp_lt_u32_e32 vcc, s0, v0
	s_mov_b64 s[10:11], -1
	v_mov_b32_e32 v2, v100
	s_and_saveexec_b64 s[8:9], vcc
	s_cbranch_execz .LBB0_157
	v_lshrrev_b32_e32 v0, 9, v0
	v_add_u32_e32 v2, -1, v0
	v_add_u32_e32 v101, 0x200, v100
	v_lshrrev_b32_e32 v3, 1, v2
	v_add_u32_e32 v4, 1, v3
	v_cmp_lt_u32_e32 vcc, 13, v2
	v_mov_b32_e32 v7, 0
	v_mov_b64_e32 v[2:3], v[100:101]
	s_and_saveexec_b64 s[10:11], vcc
	s_cbranch_execz .LBB0_153
	v_and_b32_e32 v5, -8, v4
	v_lshl_add_u32 v6, v100, 2, 0
	s_mov_b32 s0, 0
	s_mov_b64 s[74:75], 0
	v_mov_b64_e32 v[2:3], v[100:101]

.LBB0_245:
	s_or_b64 exec, exec, s[76:77]
	s_waitcnt vmcnt(0) lgkmcnt(0)
	s_barrier
	s_mov_b64 s[4:5], exec
	v_readlane_b32 s0, v255, 30
	v_readlane_b32 s1, v255, 31
	s_and_b64 s[0:1], s[4:5], s[0:1]
	s_mov_b64 exec, s[0:1]
	s_cbranch_execz .Lgs4_done
	s_mov_b64 exec, 1
	v_readlane_b32 s6, v255, 40
	v_readlane_b32 s7, v255, 41
	v_readlane_b32 s8, v255, 42
	s_nop 3
	s_add_u32 s6, s6, 0x2480000
	s_addc_u32 s7, s7, 0
	s_and_b32 s8, s8, 7
	s_lshl_b32 s8, s8, 8
	v_mov_b32_e32 v0, s8
	v_mov_b32_e32 v2, 1
	s_nop 1
	global_load_dword v3, v0, s[6:7] offset:2048 sc1
	buffer_wbl2 sc1
	s_waitcnt vmcnt(0)
	global_atomic_add v2, v0, v2, s[6:7] sc0
	s_waitcnt vmcnt(0)
	v_readfirstlane_b32 s9, v2
	v_readfirstlane_b32 s10, v3
	s_and_b32 s9, s9, 31
	s_cmp_lg_u32 s9, 31
	s_cbranch_scc1 .Lgs4_poll
	v_mov_b32_e32 v2, 1
	v_mov_b32_e32 v3, 0x1000
	s_nop 1
	global_atomic_add v2, v3, v2, s[6:7] sc0
	s_waitcnt vmcnt(0)
	v_readfirstlane_b32 s9, v2
	s_and_b32 s9, s9, 7
	s_cmp_lg_u32 s9, 7
	s_cbranch_scc1 .Lgs4_poll
	v_mov_b32_e32 v2, 1
	v_mov_b32_e32 v3, 0
	s_nop 1
	global_atomic_add v3, v2, s[6:7] offset:2048
	global_atomic_add v3, v2, s[6:7] offset:2304
	global_atomic_add v3, v2, s[6:7] offset:2560
	global_atomic_add v3, v2, s[6:7] offset:2816
	global_atomic_add v3, v2, s[6:7] offset:3072
	global_atomic_add v3, v2, s[6:7] offset:3328
	global_atomic_add v3, v2, s[6:7] offset:3584
	global_atomic_add v3, v2, s[6:7] offset:3840

.Lgs4_done:
	s_mov_b64 exec, s[4:5]
	s_mov_b32 s0, s59
	s_barrier
	v_mov_b32_e32 v13, v174
	s_cmpk_lt_i32 s0, 0xc0
	s_cselect_b64 s[4:5], -1, 0
	s_cmpk_gt_i32 s0, 0xbf
	v_readfirstlane_b32 s20, v13
	s_cbranch_scc1 .LBB0_259
	s_ashr_i32 s1, s0, 31
	s_lshr_b32 s1, s1, 29
	s_add_i32 s1, s0, s1
	s_ashr_i32 s2, s1, 3
	s_and_b32 s1, s1, -8
	s_sub_i32 s1, s0, s1
	s_cmp_lt_i32 s1, 0
	s_cselect_b32 s6, 25, 24
	s_mul_i32 s1, s1, s6
	s_add_i32 s1, s1, s2
	s_ashr_i32 s2, s1, 31
	s_lshr_b32 s2, s2, 27
	s_add_i32 s2, s1, s2
	s_ashr_i32 s6, s2, 5
	s_and_b32 s2, s2, 0xffe0
	s_sub_i32 s1, s1, s2
	s_bfe_i32 s2, s1, 0x80000
	s_bfe_u32 s2, s2, 0x3000c
	s_add_i32 s2, s1, s2
	s_bfe_i32 s7, s2, 0x80000
	s_and_b32 s2, s2, 0xf8
	s_sub_i32 s1, s1, s2
	s_lshl_b32 s6, s6, 3
	s_sext_i32_i16 s7, s7
	s_sext_i32_i8 s1, s1
	s_add_i32 s6, s6, s1
	s_ashr_i32 s80, s7, 3

.LBB0_307:
	s_waitcnt vmcnt(0) lgkmcnt(0)
	s_barrier
	s_mov_b64 s[4:5], exec
	v_readlane_b32 s0, v255, 30
	v_readlane_b32 s1, v255, 31
	v_readlane_b32 s64, v255, 43
	v_readlane_b32 s65, v255, 44
	v_readlane_b32 s66, v255, 45
	v_readlane_b32 s67, v255, 46
	v_readlane_b32 s68, v255, 47
	v_readlane_b32 s69, v255, 48
	v_readlane_b32 s70, v255, 49
	v_readlane_b32 s71, v255, 50
	v_readlane_b32 s72, v255, 51
	v_readlane_b32 s73, v255, 52
	v_readlane_b32 s74, v255, 53
	v_readlane_b32 s75, v255, 54
	v_readlane_b32 s76, v255, 55
	v_readlane_b32 s77, v255, 56
	v_readlane_b32 s78, v255, 57
	v_readlane_b32 s79, v255, 58
	s_and_b64 s[0:1], s[4:5], s[0:1]
	s_mov_b64 exec, s[0:1]
	s_cbranch_execz .Lgs5_done
	s_mov_b64 exec, 1
	v_readlane_b32 s6, v255, 40
	v_readlane_b32 s7, v255, 41
	v_readlane_b32 s8, v255, 42
	s_nop 3
	s_add_u32 s6, s6, 0x2480000
	s_addc_u32 s7, s7, 0
	s_and_b32 s8, s8, 7
	s_lshl_b32 s8, s8, 8
	v_mov_b32_e32 v0, s8
	v_mov_b32_e32 v2, 1
	s_nop 1
	global_load_dword v3, v0, s[6:7] offset:2048 sc1
	buffer_wbl2 sc1
	s_waitcnt vmcnt(0)
	global_atomic_add v2, v0, v2, s[6:7] sc0
	s_waitcnt vmcnt(0)
	v_readfirstlane_b32 s9, v2
	v_readfirstlane_b32 s10, v3
	s_and_b32 s9, s9, 31
	s_cmp_lg_u32 s9, 31
	s_cbranch_scc1 .Lgs5_poll
	v_mov_b32_e32 v2, 1
	v_mov_b32_e32 v3, 0x1000
	s_nop 1
	global_atomic_add v2, v3, v2, s[6:7] sc0
	s_waitcnt vmcnt(0)
	v_readfirstlane_b32 s9, v2
	s_and_b32 s9, s9, 7
	s_cmp_lg_u32 s9, 7
	s_cbranch_scc1 .Lgs5_poll
	v_mov_b32_e32 v2, 1
	v_mov_b32_e32 v3, 0
	s_nop 1
	global_atomic_add v3, v2, s[6:7] offset:2048
	global_atomic_add v3, v2, s[6:7] offset:2304
	global_atomic_add v3, v2, s[6:7] offset:2560
	global_atomic_add v3, v2, s[6:7] offset:2816
	global_atomic_add v3, v2, s[6:7] offset:3072
	global_atomic_add v3, v2, s[6:7] offset:3328
	global_atomic_add v3, v2, s[6:7] offset:3584
	global_atomic_add v3, v2, s[6:7] offset:3840

.Lgs5_done:
	s_branch .LBB0_53
